# P5 Q/K epilogue: all rope cos/sin loads hoisted to the front (latent tiles), the 7 per-row-group vmcnt(0) waits dropped, first wait only for latent tiles
# speedup vs baseline: 1.0424x; 1.0014x over previous
.LBB0_539:
	v_cndmask_b32_e64 v130, 0, 1, s[14:15]
	v_cmp_ne_u32_e64 s[8:9], 1, v130
	s_andn2_b64 vcc, exec, s[14:15]
	v_add_u32_e32 v162, s67, v167
	s_cbranch_vccnz .LBB0_541
	v_lshrrev_b32_e32 v130, 6, v162
	v_cndmask_b32_e64 v130, v1, v130, s[0:1]
	v_lshlrev_b32_e32 v142, 6, v130
	v_lshl_add_u64 v[130:131], v[146:147], 0, v[142:143]
	v_lshl_add_u64 v[132:133], v[148:149], 0, v[142:143]
	global_load_dwordx4 v[134:137], v[132:133], off
	s_nop 0
	global_load_dwordx4 v[130:133], v[130:131], off
	v_mov_b32_e32 v185, 0
	v_add_u32_e32 v184, s67, v173
	v_lshrrev_b32_e32 v184, 6, v184
	v_cndmask_b32_e64 v184, v145, v184, s[0:1]
	v_lshlrev_b32_e32 v184, 6, v184
	v_lshl_add_u64 v[186:187], v[148:149], 0, v[184:185]
	v_lshl_add_u64 v[188:189], v[146:147], 0, v[184:185]
	global_load_dwordx4 v[196:199], v[186:187], off
	global_load_dwordx4 v[192:195], v[188:189], off
	v_add_u32_e32 v184, s67, v174
	v_lshrrev_b32_e32 v184, 6, v184
	v_cndmask_b32_e64 v184, v165, v184, s[0:1]
	v_lshlrev_b32_e32 v184, 6, v184
	v_lshl_add_u64 v[186:187], v[148:149], 0, v[184:185]
	v_lshl_add_u64 v[188:189], v[146:147], 0, v[184:185]
	global_load_dwordx4 v[204:207], v[186:187], off
	global_load_dwordx4 v[200:203], v[188:189], off
	v_add_u32_e32 v184, s67, v175
	v_lshrrev_b32_e32 v184, 6, v184
	v_cndmask_b32_e64 v184, v166, v184, s[0:1]
	v_lshlrev_b32_e32 v184, 6, v184
	v_lshl_add_u64 v[186:187], v[148:149], 0, v[184:185]
	v_lshl_add_u64 v[188:189], v[146:147], 0, v[184:185]
	global_load_dwordx4 v[212:215], v[186:187], off
	global_load_dwordx4 v[208:211], v[188:189], off
	v_add_u32_e32 v184, s67, v176
	v_lshrrev_b32_e32 v184, 6, v184
	v_cndmask_b32_e64 v184, v1, v184, s[0:1]
	v_lshlrev_b32_e32 v184, 6, v184
	v_lshl_add_u64 v[186:187], v[148:149], 0, v[184:185]
	v_lshl_add_u64 v[188:189], v[146:147], 0, v[184:185]
	global_load_dwordx4 v[220:223], v[186:187], off
	global_load_dwordx4 v[216:219], v[188:189], off
	v_add_u32_e32 v184, s67, v177
	v_lshrrev_b32_e32 v184, 6, v184
	v_cndmask_b32_e64 v184, v145, v184, s[0:1]
	v_lshlrev_b32_e32 v184, 6, v184
	v_lshl_add_u64 v[186:187], v[148:149], 0, v[184:185]
	v_lshl_add_u64 v[188:189], v[146:147], 0, v[184:185]
	global_load_dwordx4 v[228:231], v[186:187], off
	global_load_dwordx4 v[224:227], v[188:189], off
	v_add_u32_e32 v184, s67, v178
	v_lshrrev_b32_e32 v184, 6, v184
	v_cndmask_b32_e64 v184, v165, v184, s[0:1]
	v_lshlrev_b32_e32 v184, 6, v184
	v_lshl_add_u64 v[186:187], v[148:149], 0, v[184:185]
	v_lshl_add_u64 v[188:189], v[146:147], 0, v[184:185]
	global_load_dwordx4 v[236:239], v[186:187], off
	global_load_dwordx4 v[232:235], v[188:189], off
	v_add_u32_e32 v184, s67, v179
	v_lshrrev_b32_e32 v184, 6, v184
	v_cndmask_b32_e64 v184, v166, v184, s[0:1]
	v_lshlrev_b32_e32 v184, 6, v184
	v_lshl_add_u64 v[186:187], v[148:149], 0, v[184:185]
	v_lshl_add_u64 v[188:189], v[146:147], 0, v[184:185]
	global_load_dwordx4 v[250:253], v[186:187], off
	global_load_dwordx4 v[246:249], v[188:189], off
	s_branch .LBB0_542

.LBB0_552:
	s_cmp_lt_u32 s27, 0x2000
	s_cbranch_scc1 .Lqk_nw0
	s_waitcnt vmcnt(0)
.Lqk_nw0:
	v_pk_mul_f32 v[184:185], v[124:125], v[132:133]
	v_pk_mul_f32 v[186:187], v[122:123], v[130:131]
	v_pk_mul_f32 v[124:125], v[124:125], v[136:137]
	v_pk_mul_f32 v[122:123], v[122:123], v[134:135]
	s_lshl_b32 s24, s24, 1
	v_pk_fma_f32 v[186:187], v[126:127], v[134:135], v[186:187] neg_lo:[0,0,1] neg_hi:[0,0,1]
	v_pk_fma_f32 v[184:185], v[128:129], v[136:137], v[184:185] neg_lo:[0,0,1] neg_hi:[0,0,1]
	v_pk_fma_f32 v[122:123], v[126:127], v[130:131], v[122:123]
	v_pk_fma_f32 v[124:125], v[128:129], v[132:133], v[124:125]
	v_lshl_add_u64 v[160:161], v[160:161], 0, s[24:25]
	s_lshl_b32 s76, s96, 1
	s_mov_b32 s77, s25
	v_pk_mul_f32 v[126:127], v[186:187], s[64:65] op_sel_hi:[1,0]
	v_pk_mul_f32 v[128:129], v[184:185], s[64:65] op_sel_hi:[1,0]
	v_pk_mul_f32 v[188:189], v[122:123], s[64:65] op_sel_hi:[1,0]
	v_pk_mul_f32 v[190:191], v[124:125], s[64:65] op_sel_hi:[1,0]
	v_lshl_add_u64 v[160:161], v[160:161], 0, s[76:77]
	v_lshlrev_b32_e32 v142, 1, v144
	v_cndmask_b32_e64 v125, v125, v191, s[6:7]
	v_cndmask_b32_e64 v159, v124, v190, s[6:7]
	v_cndmask_b32_e64 v124, v123, v189, s[6:7]
	v_cndmask_b32_e64 v183, v122, v188, s[6:7]
	v_cndmask_b32_e64 v123, v185, v129, s[6:7]
	v_cndmask_b32_e64 v128, v184, v128, s[6:7]
	v_cndmask_b32_e64 v122, v187, v127, s[6:7]
	v_cndmask_b32_e64 v126, v186, v126, s[6:7]
	s_xor_b64 s[14:15], s[10:11], -1
	v_lshl_add_u64 v[160:161], v[160:161], 0, v[142:143]
	v_cvt_pk_bf16_f32 v122, v126, v122
	v_cvt_pk_bf16_f32 v123, v128, v123
	v_cvt_pk_bf16_f32 v124, v183, v124
	v_cvt_pk_bf16_f32 v125, v159, v125
	global_store_dwordx4 v[160:161], v[122:125], off
	s_andn2_b64 vcc, exec, s[14:15]
	s_nop 0
	v_cndmask_b32_e64 v122, 0, 1, s[14:15]
	v_cmp_ne_u32_e64 s[10:11], 1, v122
	s_cbranch_vccnz .LBB0_554
	v_mov_b32_e32 v159, v143
	v_lshl_add_u64 v[122:123], v[162:163], 0, v[158:159]
	global_store_dwordx4 v[122:123], v[118:121], off offset:512 nt
	global_store_dwordx4 v[122:123], v[114:117], off offset:576 nt
.LBB0_554:
	v_pk_mul_f32 v[122:123], v[116:117], v[132:133]
	v_pk_mul_f32 v[124:125], v[114:115], v[130:131]
	v_pk_mul_f32 v[116:117], v[116:117], v[136:137]
	v_pk_mul_f32 v[114:115], v[114:115], v[134:135]
	v_pk_fma_f32 v[122:123], v[120:121], v[136:137], v[122:123] neg_lo:[0,0,1] neg_hi:[0,0,1]
	v_pk_fma_f32 v[124:125], v[118:119], v[134:135], v[124:125] neg_lo:[0,0,1] neg_hi:[0,0,1]
	v_pk_fma_f32 v[116:117], v[120:121], v[132:133], v[116:117]
	v_pk_fma_f32 v[114:115], v[118:119], v[130:131], v[114:115]
	v_pk_mul_f32 v[118:119], v[124:125], s[64:65] op_sel_hi:[1,0]
	v_pk_mul_f32 v[120:121], v[122:123], s[64:65] op_sel_hi:[1,0]
	v_pk_mul_f32 v[126:127], v[114:115], s[64:65] op_sel_hi:[1,0]
	v_pk_mul_f32 v[128:129], v[116:117], s[64:65] op_sel_hi:[1,0]
	v_cndmask_b32_e64 v126, v114, v126, s[6:7]
	v_cndmask_b32_e64 v117, v117, v129, s[6:7]
	v_cndmask_b32_e64 v128, v116, v128, s[6:7]
	v_cndmask_b32_e64 v116, v115, v127, s[6:7]
	v_cndmask_b32_e64 v115, v123, v121, s[6:7]
	v_cndmask_b32_e64 v120, v122, v120, s[6:7]
	v_cndmask_b32_e64 v114, v125, v119, s[6:7]
	v_cndmask_b32_e64 v118, v124, v118, s[6:7]
	v_cvt_pk_bf16_f32 v114, v118, v114
	v_cvt_pk_bf16_f32 v115, v120, v115
	v_cvt_pk_bf16_f32 v116, v126, v116
	v_cvt_pk_bf16_f32 v117, v128, v117
	s_and_b64 vcc, exec, s[8:9]
	v_add_u32_e32 v126, s67, v173
	global_store_dwordx4 v[160:161], v[114:117], off offset:256
	s_cbranch_vccnz .LBB0_556
	s_nop 0
	s_branch .LBB0_557
.LBB0_556:
	v_mov_b32_e32 v196, 1.0
	v_mov_b32_e32 v192, 0
	v_mov_b32_e32 v193, v192
	v_mov_b32_e32 v194, v192
	v_mov_b32_e32 v195, v192
	v_mov_b32_e32 v197, v196
	v_mov_b32_e32 v198, v196
	v_mov_b32_e32 v199, v196

.LBB0_565:
	v_lshl_add_u64 v[122:123], v[124:125], 0, s[24:25]
	s_nop 0
	v_pk_mul_f32 v[124:125], v[108:109], v[194:195]
	v_pk_mul_f32 v[128:129], v[106:107], v[192:193]
	v_pk_mul_f32 v[108:109], v[108:109], v[198:199]
	v_pk_mul_f32 v[106:107], v[106:107], v[196:197]
	v_pk_fma_f32 v[128:129], v[110:111], v[196:197], v[128:129] neg_lo:[0,0,1] neg_hi:[0,0,1]
	v_pk_fma_f32 v[124:125], v[112:113], v[198:199], v[124:125] neg_lo:[0,0,1] neg_hi:[0,0,1]
	v_pk_fma_f32 v[106:107], v[110:111], v[192:193], v[106:107]
	v_pk_fma_f32 v[108:109], v[112:113], v[194:195], v[108:109]
	s_mov_b32 s77, s25
	v_pk_mul_f32 v[110:111], v[128:129], s[64:65] op_sel_hi:[1,0]
	v_pk_mul_f32 v[112:113], v[124:125], s[64:65] op_sel_hi:[1,0]
	v_pk_mul_f32 v[130:131], v[106:107], s[64:65] op_sel_hi:[1,0]
	v_pk_mul_f32 v[132:133], v[108:109], s[64:65] op_sel_hi:[1,0]
	v_lshl_add_u64 v[122:123], v[122:123], 0, s[76:77]
	v_cndmask_b32_e64 v109, v109, v133, s[6:7]
	v_cndmask_b32_e64 v132, v108, v132, s[6:7]
	v_cndmask_b32_e64 v108, v107, v131, s[6:7]
	v_cndmask_b32_e64 v130, v106, v130, s[6:7]
	v_cndmask_b32_e64 v107, v125, v113, s[6:7]
	v_cndmask_b32_e64 v112, v124, v112, s[6:7]
	v_cndmask_b32_e64 v106, v129, v111, s[6:7]
	v_cndmask_b32_e64 v110, v128, v110, s[6:7]
	v_lshl_add_u64 v[122:123], v[122:123], 0, v[142:143]
	v_cvt_pk_bf16_f32 v106, v110, v106
	v_cvt_pk_bf16_f32 v107, v112, v107
	v_cvt_pk_bf16_f32 v108, v130, v108
	v_cvt_pk_bf16_f32 v109, v132, v109
	s_and_b64 vcc, exec, s[10:11]
	global_store_dwordx4 v[122:123], v[106:109], off
	s_cbranch_vccnz .LBB0_567
	v_mov_b32_e32 v159, v143
	v_lshl_add_u64 v[106:107], v[126:127], 0, v[158:159]
	global_store_dwordx4 v[106:107], v[102:105], off offset:512 nt
	global_store_dwordx4 v[106:107], v[98:101], off offset:576 nt
.LBB0_567:
	s_nop 0
	v_pk_mul_f32 v[106:107], v[100:101], v[194:195]
	v_pk_mul_f32 v[108:109], v[98:99], v[192:193]
	v_pk_mul_f32 v[100:101], v[100:101], v[198:199]
	v_pk_mul_f32 v[98:99], v[98:99], v[196:197]
	v_pk_fma_f32 v[106:107], v[104:105], v[198:199], v[106:107] neg_lo:[0,0,1] neg_hi:[0,0,1]
	v_pk_fma_f32 v[108:109], v[102:103], v[196:197], v[108:109] neg_lo:[0,0,1] neg_hi:[0,0,1]
	v_pk_fma_f32 v[100:101], v[104:105], v[194:195], v[100:101]
	v_pk_fma_f32 v[98:99], v[102:103], v[192:193], v[98:99]
	v_pk_mul_f32 v[102:103], v[108:109], s[64:65] op_sel_hi:[1,0]
	v_pk_mul_f32 v[104:105], v[106:107], s[64:65] op_sel_hi:[1,0]
	v_pk_mul_f32 v[110:111], v[98:99], s[64:65] op_sel_hi:[1,0]
	v_pk_mul_f32 v[112:113], v[100:101], s[64:65] op_sel_hi:[1,0]
	v_cndmask_b32_e64 v110, v98, v110, s[6:7]
	v_cndmask_b32_e64 v101, v101, v113, s[6:7]
	v_cndmask_b32_e64 v112, v100, v112, s[6:7]
	v_cndmask_b32_e64 v100, v99, v111, s[6:7]
	v_cndmask_b32_e64 v99, v107, v105, s[6:7]
	v_cndmask_b32_e64 v104, v106, v104, s[6:7]
	v_cndmask_b32_e64 v98, v109, v103, s[6:7]
	v_cndmask_b32_e64 v102, v108, v102, s[6:7]
	v_cvt_pk_bf16_f32 v98, v102, v98
	v_cvt_pk_bf16_f32 v99, v104, v99
	v_cvt_pk_bf16_f32 v100, v110, v100
	v_cvt_pk_bf16_f32 v101, v112, v101
	s_and_b64 vcc, exec, s[8:9]
	v_add_u32_e32 v110, s67, v174
	global_store_dwordx4 v[122:123], v[98:101], off offset:256
	s_cbranch_vccnz .LBB0_573
	s_nop 0
	v_add_u32_e32 v106, s27, v174
	s_and_b64 vcc, exec, s[14:15]
	s_mov_b64 s[78:79], -1
	s_cbranch_vccz .LBB0_574

.LBB0_573:
	v_mov_b32_e32 v204, 1.0
	v_mov_b32_e32 v200, 0
	v_mov_b32_e32 v201, v200
	v_mov_b32_e32 v202, v200
	v_mov_b32_e32 v203, v200
	v_mov_b32_e32 v205, v204
	v_mov_b32_e32 v206, v204
	v_mov_b32_e32 v207, v204
	v_add_u32_e32 v106, s27, v174
	s_and_b64 vcc, exec, s[14:15]
	s_mov_b64 s[78:79], -1
	s_cbranch_vccnz .LBB0_569

.LBB0_581:
	v_lshl_add_u64 v[106:107], v[108:109], 0, s[24:25]
	s_nop 0
	v_pk_mul_f32 v[108:109], v[92:93], v[202:203]
	v_pk_mul_f32 v[112:113], v[90:91], v[200:201]
	v_pk_mul_f32 v[92:93], v[92:93], v[206:207]
	v_pk_mul_f32 v[90:91], v[90:91], v[204:205]
	v_pk_fma_f32 v[112:113], v[94:95], v[204:205], v[112:113] neg_lo:[0,0,1] neg_hi:[0,0,1]
	v_pk_fma_f32 v[108:109], v[96:97], v[206:207], v[108:109] neg_lo:[0,0,1] neg_hi:[0,0,1]
	v_pk_fma_f32 v[90:91], v[94:95], v[200:201], v[90:91]
	v_pk_fma_f32 v[92:93], v[96:97], v[202:203], v[92:93]
	s_mov_b32 s77, s25
	v_pk_mul_f32 v[94:95], v[112:113], s[64:65] op_sel_hi:[1,0]
	v_pk_mul_f32 v[96:97], v[108:109], s[64:65] op_sel_hi:[1,0]
	v_pk_mul_f32 v[114:115], v[90:91], s[64:65] op_sel_hi:[1,0]
	v_pk_mul_f32 v[116:117], v[92:93], s[64:65] op_sel_hi:[1,0]
	v_lshl_add_u64 v[106:107], v[106:107], 0, s[76:77]
	v_cndmask_b32_e64 v93, v93, v117, s[6:7]
	v_cndmask_b32_e64 v116, v92, v116, s[6:7]
	v_cndmask_b32_e64 v92, v91, v115, s[6:7]
	v_cndmask_b32_e64 v114, v90, v114, s[6:7]
	v_cndmask_b32_e64 v91, v109, v97, s[6:7]
	v_cndmask_b32_e64 v96, v108, v96, s[6:7]
	v_cndmask_b32_e64 v90, v113, v95, s[6:7]
	v_cndmask_b32_e64 v94, v112, v94, s[6:7]
	v_lshl_add_u64 v[106:107], v[106:107], 0, v[142:143]
	v_cvt_pk_bf16_f32 v90, v94, v90
	v_cvt_pk_bf16_f32 v91, v96, v91
	v_cvt_pk_bf16_f32 v92, v114, v92
	v_cvt_pk_bf16_f32 v93, v116, v93
	s_and_b64 vcc, exec, s[10:11]
	global_store_dwordx4 v[106:107], v[90:93], off
	s_cbranch_vccnz .LBB0_583
	v_mov_b32_e32 v159, v143
	v_lshl_add_u64 v[90:91], v[110:111], 0, v[158:159]
	global_store_dwordx4 v[90:91], v[86:89], off offset:512 nt
	global_store_dwordx4 v[90:91], v[82:85], off offset:576 nt
.LBB0_583:
	s_nop 0
	v_pk_mul_f32 v[90:91], v[84:85], v[202:203]
	v_pk_mul_f32 v[92:93], v[82:83], v[200:201]
	v_pk_mul_f32 v[84:85], v[84:85], v[206:207]
	v_pk_mul_f32 v[82:83], v[82:83], v[204:205]
	v_pk_fma_f32 v[90:91], v[88:89], v[206:207], v[90:91] neg_lo:[0,0,1] neg_hi:[0,0,1]
	v_pk_fma_f32 v[92:93], v[86:87], v[204:205], v[92:93] neg_lo:[0,0,1] neg_hi:[0,0,1]
	v_pk_fma_f32 v[84:85], v[88:89], v[202:203], v[84:85]
	v_pk_fma_f32 v[82:83], v[86:87], v[200:201], v[82:83]
	v_pk_mul_f32 v[86:87], v[92:93], s[64:65] op_sel_hi:[1,0]
	v_pk_mul_f32 v[88:89], v[90:91], s[64:65] op_sel_hi:[1,0]
	v_pk_mul_f32 v[94:95], v[82:83], s[64:65] op_sel_hi:[1,0]
	v_pk_mul_f32 v[96:97], v[84:85], s[64:65] op_sel_hi:[1,0]
	v_cndmask_b32_e64 v94, v82, v94, s[6:7]
	v_cndmask_b32_e64 v85, v85, v97, s[6:7]
	v_cndmask_b32_e64 v96, v84, v96, s[6:7]
	v_cndmask_b32_e64 v84, v83, v95, s[6:7]
	v_cndmask_b32_e64 v83, v91, v89, s[6:7]
	v_cndmask_b32_e64 v88, v90, v88, s[6:7]
	v_cndmask_b32_e64 v82, v93, v87, s[6:7]
	v_cndmask_b32_e64 v86, v92, v86, s[6:7]
	v_cvt_pk_bf16_f32 v82, v86, v82
	v_cvt_pk_bf16_f32 v83, v88, v83
	v_cvt_pk_bf16_f32 v84, v94, v84
	v_cvt_pk_bf16_f32 v85, v96, v85
	s_and_b64 vcc, exec, s[8:9]
	v_add_u32_e32 v94, s67, v175
	global_store_dwordx4 v[106:107], v[82:85], off offset:256
	s_cbranch_vccnz .LBB0_587
	s_nop 0
	v_add_u32_e32 v90, s27, v175
	s_and_b64 vcc, exec, s[14:15]
	s_mov_b64 s[78:79], -1
	s_cbranch_vccz .LBB0_588

.LBB0_587:
	v_mov_b32_e32 v212, 1.0
	v_mov_b32_e32 v208, 0
	v_mov_b32_e32 v209, v208
	v_mov_b32_e32 v210, v208
	v_mov_b32_e32 v211, v208
	v_mov_b32_e32 v213, v212
	v_mov_b32_e32 v214, v212
	v_mov_b32_e32 v215, v212
	v_add_u32_e32 v90, s27, v175
	s_and_b64 vcc, exec, s[14:15]
	s_mov_b64 s[78:79], -1
	s_cbranch_vccnz .LBB0_585

.LBB0_595:
	v_lshl_add_u64 v[90:91], v[92:93], 0, s[24:25]
	s_nop 0
	v_pk_mul_f32 v[92:93], v[76:77], v[210:211]
	v_pk_mul_f32 v[96:97], v[74:75], v[208:209]
	v_pk_mul_f32 v[76:77], v[76:77], v[214:215]
	v_pk_mul_f32 v[74:75], v[74:75], v[212:213]
	v_pk_fma_f32 v[96:97], v[78:79], v[212:213], v[96:97] neg_lo:[0,0,1] neg_hi:[0,0,1]
	v_pk_fma_f32 v[92:93], v[80:81], v[214:215], v[92:93] neg_lo:[0,0,1] neg_hi:[0,0,1]
	v_pk_fma_f32 v[74:75], v[78:79], v[208:209], v[74:75]
	v_pk_fma_f32 v[76:77], v[80:81], v[210:211], v[76:77]
	s_mov_b32 s77, s25
	v_pk_mul_f32 v[78:79], v[96:97], s[64:65] op_sel_hi:[1,0]
	v_pk_mul_f32 v[80:81], v[92:93], s[64:65] op_sel_hi:[1,0]
	v_pk_mul_f32 v[98:99], v[74:75], s[64:65] op_sel_hi:[1,0]
	v_pk_mul_f32 v[100:101], v[76:77], s[64:65] op_sel_hi:[1,0]
	v_lshl_add_u64 v[90:91], v[90:91], 0, s[76:77]
	v_cndmask_b32_e64 v77, v77, v101, s[6:7]
	v_cndmask_b32_e64 v100, v76, v100, s[6:7]
	v_cndmask_b32_e64 v76, v75, v99, s[6:7]
	v_cndmask_b32_e64 v98, v74, v98, s[6:7]
	v_cndmask_b32_e64 v75, v93, v81, s[6:7]
	v_cndmask_b32_e64 v80, v92, v80, s[6:7]
	v_cndmask_b32_e64 v74, v97, v79, s[6:7]
	v_cndmask_b32_e64 v78, v96, v78, s[6:7]
	v_lshl_add_u64 v[90:91], v[90:91], 0, v[142:143]
	v_cvt_pk_bf16_f32 v74, v78, v74
	v_cvt_pk_bf16_f32 v75, v80, v75
	v_cvt_pk_bf16_f32 v76, v98, v76
	v_cvt_pk_bf16_f32 v77, v100, v77
	s_and_b64 vcc, exec, s[10:11]
	global_store_dwordx4 v[90:91], v[74:77], off
	s_cbranch_vccnz .LBB0_597
	v_mov_b32_e32 v159, v143
	v_lshl_add_u64 v[74:75], v[94:95], 0, v[158:159]
	global_store_dwordx4 v[74:75], v[70:73], off offset:512 nt
	global_store_dwordx4 v[74:75], v[66:69], off offset:576 nt
.LBB0_597:
	s_nop 0
	v_pk_mul_f32 v[74:75], v[68:69], v[210:211]
	v_pk_mul_f32 v[76:77], v[66:67], v[208:209]
	v_pk_mul_f32 v[68:69], v[68:69], v[214:215]
	v_pk_mul_f32 v[66:67], v[66:67], v[212:213]
	v_pk_fma_f32 v[74:75], v[72:73], v[214:215], v[74:75] neg_lo:[0,0,1] neg_hi:[0,0,1]
	v_pk_fma_f32 v[76:77], v[70:71], v[212:213], v[76:77] neg_lo:[0,0,1] neg_hi:[0,0,1]
	v_pk_fma_f32 v[68:69], v[72:73], v[210:211], v[68:69]
	v_pk_fma_f32 v[66:67], v[70:71], v[208:209], v[66:67]
	v_pk_mul_f32 v[70:71], v[76:77], s[64:65] op_sel_hi:[1,0]
	v_pk_mul_f32 v[72:73], v[74:75], s[64:65] op_sel_hi:[1,0]
	v_pk_mul_f32 v[78:79], v[66:67], s[64:65] op_sel_hi:[1,0]
	v_pk_mul_f32 v[80:81], v[68:69], s[64:65] op_sel_hi:[1,0]
	v_cndmask_b32_e64 v78, v66, v78, s[6:7]
	v_cndmask_b32_e64 v69, v69, v81, s[6:7]
	v_cndmask_b32_e64 v80, v68, v80, s[6:7]
	v_cndmask_b32_e64 v68, v67, v79, s[6:7]
	v_cndmask_b32_e64 v67, v75, v73, s[6:7]
	v_cndmask_b32_e64 v72, v74, v72, s[6:7]
	v_cndmask_b32_e64 v66, v77, v71, s[6:7]
	v_cndmask_b32_e64 v70, v76, v70, s[6:7]
	v_cvt_pk_bf16_f32 v66, v70, v66
	v_cvt_pk_bf16_f32 v67, v72, v67
	v_cvt_pk_bf16_f32 v68, v78, v68
	v_cvt_pk_bf16_f32 v69, v80, v69
	s_and_b64 vcc, exec, s[8:9]
	v_add_u32_e32 v78, s67, v176
	global_store_dwordx4 v[90:91], v[66:69], off offset:256
	s_cbranch_vccnz .LBB0_601
	s_nop 0
	v_add_u32_e32 v74, s27, v176
	s_and_b64 vcc, exec, s[14:15]
	s_mov_b64 s[78:79], -1
	s_cbranch_vccz .LBB0_602

.LBB0_601:
	v_mov_b32_e32 v220, 1.0
	v_mov_b32_e32 v216, 0
	v_mov_b32_e32 v217, v216
	v_mov_b32_e32 v218, v216
	v_mov_b32_e32 v219, v216
	v_mov_b32_e32 v221, v220
	v_mov_b32_e32 v222, v220
	v_mov_b32_e32 v223, v220
	v_add_u32_e32 v74, s27, v176
	s_and_b64 vcc, exec, s[14:15]
	s_mov_b64 s[78:79], -1
	s_cbranch_vccnz .LBB0_599

.LBB0_609:
	v_lshl_add_u64 v[74:75], v[76:77], 0, s[24:25]
	s_nop 0
	v_pk_mul_f32 v[76:77], v[60:61], v[218:219]
	v_pk_mul_f32 v[80:81], v[58:59], v[216:217]
	v_pk_mul_f32 v[60:61], v[60:61], v[222:223]
	v_pk_mul_f32 v[58:59], v[58:59], v[220:221]
	v_pk_fma_f32 v[80:81], v[62:63], v[220:221], v[80:81] neg_lo:[0,0,1] neg_hi:[0,0,1]
	v_pk_fma_f32 v[76:77], v[64:65], v[222:223], v[76:77] neg_lo:[0,0,1] neg_hi:[0,0,1]
	v_pk_fma_f32 v[58:59], v[62:63], v[216:217], v[58:59]
	v_pk_fma_f32 v[60:61], v[64:65], v[218:219], v[60:61]
	s_mov_b32 s77, s25
	v_pk_mul_f32 v[62:63], v[80:81], s[64:65] op_sel_hi:[1,0]
	v_pk_mul_f32 v[64:65], v[76:77], s[64:65] op_sel_hi:[1,0]
	v_pk_mul_f32 v[82:83], v[58:59], s[64:65] op_sel_hi:[1,0]
	v_pk_mul_f32 v[84:85], v[60:61], s[64:65] op_sel_hi:[1,0]
	v_lshl_add_u64 v[74:75], v[74:75], 0, s[76:77]
	v_cndmask_b32_e64 v61, v61, v85, s[6:7]
	v_cndmask_b32_e64 v84, v60, v84, s[6:7]
	v_cndmask_b32_e64 v60, v59, v83, s[6:7]
	v_cndmask_b32_e64 v82, v58, v82, s[6:7]
	v_cndmask_b32_e64 v59, v77, v65, s[6:7]
	v_cndmask_b32_e64 v64, v76, v64, s[6:7]
	v_cndmask_b32_e64 v58, v81, v63, s[6:7]
	v_cndmask_b32_e64 v62, v80, v62, s[6:7]
	v_lshl_add_u64 v[74:75], v[74:75], 0, v[142:143]
	v_cvt_pk_bf16_f32 v58, v62, v58
	v_cvt_pk_bf16_f32 v59, v64, v59
	v_cvt_pk_bf16_f32 v60, v82, v60
	v_cvt_pk_bf16_f32 v61, v84, v61
	s_and_b64 vcc, exec, s[10:11]
	global_store_dwordx4 v[74:75], v[58:61], off
	s_cbranch_vccnz .LBB0_611
	v_mov_b32_e32 v159, v143
	v_lshl_add_u64 v[58:59], v[78:79], 0, v[158:159]
	global_store_dwordx4 v[58:59], v[54:57], off offset:512 nt
	global_store_dwordx4 v[58:59], v[50:53], off offset:576 nt
.LBB0_611:
	s_nop 0
	v_pk_mul_f32 v[58:59], v[52:53], v[218:219]
	v_pk_mul_f32 v[60:61], v[50:51], v[216:217]
	v_pk_mul_f32 v[52:53], v[52:53], v[222:223]
	v_pk_mul_f32 v[50:51], v[50:51], v[220:221]
	v_pk_fma_f32 v[58:59], v[56:57], v[222:223], v[58:59] neg_lo:[0,0,1] neg_hi:[0,0,1]
	v_pk_fma_f32 v[60:61], v[54:55], v[220:221], v[60:61] neg_lo:[0,0,1] neg_hi:[0,0,1]
	v_pk_fma_f32 v[52:53], v[56:57], v[218:219], v[52:53]
	v_pk_fma_f32 v[50:51], v[54:55], v[216:217], v[50:51]
	v_pk_mul_f32 v[54:55], v[60:61], s[64:65] op_sel_hi:[1,0]
	v_pk_mul_f32 v[56:57], v[58:59], s[64:65] op_sel_hi:[1,0]
	v_pk_mul_f32 v[62:63], v[50:51], s[64:65] op_sel_hi:[1,0]
	v_pk_mul_f32 v[64:65], v[52:53], s[64:65] op_sel_hi:[1,0]
	v_cndmask_b32_e64 v62, v50, v62, s[6:7]
	v_cndmask_b32_e64 v53, v53, v65, s[6:7]
	v_cndmask_b32_e64 v64, v52, v64, s[6:7]
	v_cndmask_b32_e64 v52, v51, v63, s[6:7]
	v_cndmask_b32_e64 v51, v59, v57, s[6:7]
	v_cndmask_b32_e64 v56, v58, v56, s[6:7]
	v_cndmask_b32_e64 v50, v61, v55, s[6:7]
	v_cndmask_b32_e64 v54, v60, v54, s[6:7]
	v_cvt_pk_bf16_f32 v50, v54, v50
	v_cvt_pk_bf16_f32 v51, v56, v51
	v_cvt_pk_bf16_f32 v52, v62, v52
	v_cvt_pk_bf16_f32 v53, v64, v53
	s_and_b64 vcc, exec, s[8:9]
	v_add_u32_e32 v62, s67, v177
	global_store_dwordx4 v[74:75], v[50:53], off offset:256
	s_cbranch_vccnz .LBB0_615
	s_nop 0
	v_add_u32_e32 v58, s27, v177
	s_and_b64 vcc, exec, s[14:15]
	s_mov_b64 s[78:79], -1
	s_cbranch_vccz .LBB0_616

.LBB0_615:
	v_mov_b32_e32 v228, 1.0
	v_mov_b32_e32 v224, 0
	v_mov_b32_e32 v225, v224
	v_mov_b32_e32 v226, v224
	v_mov_b32_e32 v227, v224
	v_mov_b32_e32 v229, v228
	v_mov_b32_e32 v230, v228
	v_mov_b32_e32 v231, v228
	v_add_u32_e32 v58, s27, v177
	s_and_b64 vcc, exec, s[14:15]
	s_mov_b64 s[78:79], -1
	s_cbranch_vccnz .LBB0_613

.LBB0_623:
	v_lshl_add_u64 v[58:59], v[60:61], 0, s[24:25]
	s_nop 0
	v_pk_mul_f32 v[60:61], v[44:45], v[226:227]
	v_pk_mul_f32 v[64:65], v[42:43], v[224:225]
	v_pk_mul_f32 v[44:45], v[44:45], v[230:231]
	v_pk_mul_f32 v[42:43], v[42:43], v[228:229]
	v_pk_fma_f32 v[64:65], v[46:47], v[228:229], v[64:65] neg_lo:[0,0,1] neg_hi:[0,0,1]
	v_pk_fma_f32 v[60:61], v[48:49], v[230:231], v[60:61] neg_lo:[0,0,1] neg_hi:[0,0,1]
	v_pk_fma_f32 v[42:43], v[46:47], v[224:225], v[42:43]
	v_pk_fma_f32 v[44:45], v[48:49], v[226:227], v[44:45]
	s_mov_b32 s77, s25
	v_pk_mul_f32 v[46:47], v[64:65], s[64:65] op_sel_hi:[1,0]
	v_pk_mul_f32 v[48:49], v[60:61], s[64:65] op_sel_hi:[1,0]
	v_pk_mul_f32 v[66:67], v[42:43], s[64:65] op_sel_hi:[1,0]
	v_pk_mul_f32 v[68:69], v[44:45], s[64:65] op_sel_hi:[1,0]
	v_lshl_add_u64 v[58:59], v[58:59], 0, s[76:77]
	v_cndmask_b32_e64 v45, v45, v69, s[6:7]
	v_cndmask_b32_e64 v68, v44, v68, s[6:7]
	v_cndmask_b32_e64 v44, v43, v67, s[6:7]
	v_cndmask_b32_e64 v66, v42, v66, s[6:7]
	v_cndmask_b32_e64 v43, v61, v49, s[6:7]
	v_cndmask_b32_e64 v48, v60, v48, s[6:7]
	v_cndmask_b32_e64 v42, v65, v47, s[6:7]
	v_cndmask_b32_e64 v46, v64, v46, s[6:7]
	v_lshl_add_u64 v[58:59], v[58:59], 0, v[142:143]
	v_cvt_pk_bf16_f32 v42, v46, v42
	v_cvt_pk_bf16_f32 v43, v48, v43
	v_cvt_pk_bf16_f32 v44, v66, v44
	v_cvt_pk_bf16_f32 v45, v68, v45
	s_and_b64 vcc, exec, s[10:11]
	global_store_dwordx4 v[58:59], v[42:45], off
	s_cbranch_vccnz .LBB0_625
	v_mov_b32_e32 v159, v143
	v_lshl_add_u64 v[42:43], v[62:63], 0, v[158:159]
	global_store_dwordx4 v[42:43], v[38:41], off offset:512 nt
	global_store_dwordx4 v[42:43], v[34:37], off offset:576 nt
.LBB0_625:
	s_nop 0
	v_pk_mul_f32 v[42:43], v[36:37], v[226:227]
	v_pk_mul_f32 v[44:45], v[34:35], v[224:225]
	v_pk_mul_f32 v[36:37], v[36:37], v[230:231]
	v_pk_mul_f32 v[34:35], v[34:35], v[228:229]
	v_pk_fma_f32 v[42:43], v[40:41], v[230:231], v[42:43] neg_lo:[0,0,1] neg_hi:[0,0,1]
	v_pk_fma_f32 v[44:45], v[38:39], v[228:229], v[44:45] neg_lo:[0,0,1] neg_hi:[0,0,1]
	v_pk_fma_f32 v[36:37], v[40:41], v[226:227], v[36:37]
	v_pk_fma_f32 v[34:35], v[38:39], v[224:225], v[34:35]
	v_pk_mul_f32 v[38:39], v[44:45], s[64:65] op_sel_hi:[1,0]
	v_pk_mul_f32 v[40:41], v[42:43], s[64:65] op_sel_hi:[1,0]
	v_pk_mul_f32 v[46:47], v[34:35], s[64:65] op_sel_hi:[1,0]
	v_pk_mul_f32 v[48:49], v[36:37], s[64:65] op_sel_hi:[1,0]
	v_cndmask_b32_e64 v46, v34, v46, s[6:7]
	v_cndmask_b32_e64 v37, v37, v49, s[6:7]
	v_cndmask_b32_e64 v48, v36, v48, s[6:7]
	v_cndmask_b32_e64 v36, v35, v47, s[6:7]
	v_cndmask_b32_e64 v35, v43, v41, s[6:7]
	v_cndmask_b32_e64 v40, v42, v40, s[6:7]
	v_cndmask_b32_e64 v34, v45, v39, s[6:7]
	v_cndmask_b32_e64 v38, v44, v38, s[6:7]
	v_cvt_pk_bf16_f32 v34, v38, v34
	v_cvt_pk_bf16_f32 v35, v40, v35
	v_cvt_pk_bf16_f32 v36, v46, v36
	v_cvt_pk_bf16_f32 v37, v48, v37
	s_and_b64 vcc, exec, s[8:9]
	v_add_u32_e32 v46, s67, v178
	global_store_dwordx4 v[58:59], v[34:37], off offset:256
	s_cbranch_vccnz .LBB0_629
	s_nop 0
	v_add_u32_e32 v42, s27, v178
	s_and_b64 vcc, exec, s[14:15]
	s_mov_b64 s[78:79], -1
	s_cbranch_vccz .LBB0_630

.LBB0_629:
	v_mov_b32_e32 v236, 1.0
	v_mov_b32_e32 v232, 0
	v_mov_b32_e32 v233, v232
	v_mov_b32_e32 v234, v232
	v_mov_b32_e32 v235, v232
	v_mov_b32_e32 v237, v236
	v_mov_b32_e32 v238, v236
	v_mov_b32_e32 v239, v236
	v_add_u32_e32 v42, s27, v178
	s_and_b64 vcc, exec, s[14:15]
	s_mov_b64 s[78:79], -1
	s_cbranch_vccnz .LBB0_627

.LBB0_637:
	v_lshl_add_u64 v[42:43], v[44:45], 0, s[24:25]
	s_nop 0
	v_pk_mul_f32 v[44:45], v[28:29], v[234:235]
	v_pk_mul_f32 v[48:49], v[26:27], v[232:233]
	v_pk_mul_f32 v[28:29], v[28:29], v[238:239]
	v_pk_mul_f32 v[26:27], v[26:27], v[236:237]
	v_pk_fma_f32 v[48:49], v[30:31], v[236:237], v[48:49] neg_lo:[0,0,1] neg_hi:[0,0,1]
	v_pk_fma_f32 v[44:45], v[32:33], v[238:239], v[44:45] neg_lo:[0,0,1] neg_hi:[0,0,1]
	v_pk_fma_f32 v[26:27], v[30:31], v[232:233], v[26:27]
	v_pk_fma_f32 v[28:29], v[32:33], v[234:235], v[28:29]
	s_mov_b32 s77, s25
	v_pk_mul_f32 v[30:31], v[48:49], s[64:65] op_sel_hi:[1,0]
	v_pk_mul_f32 v[32:33], v[44:45], s[64:65] op_sel_hi:[1,0]
	v_pk_mul_f32 v[50:51], v[26:27], s[64:65] op_sel_hi:[1,0]
	v_pk_mul_f32 v[52:53], v[28:29], s[64:65] op_sel_hi:[1,0]
	v_lshl_add_u64 v[42:43], v[42:43], 0, s[76:77]
	v_cndmask_b32_e64 v29, v29, v53, s[6:7]
	v_cndmask_b32_e64 v52, v28, v52, s[6:7]
	v_cndmask_b32_e64 v28, v27, v51, s[6:7]
	v_cndmask_b32_e64 v50, v26, v50, s[6:7]
	v_cndmask_b32_e64 v27, v45, v33, s[6:7]
	v_cndmask_b32_e64 v32, v44, v32, s[6:7]
	v_cndmask_b32_e64 v26, v49, v31, s[6:7]
	v_cndmask_b32_e64 v30, v48, v30, s[6:7]
	v_lshl_add_u64 v[42:43], v[42:43], 0, v[142:143]
	v_cvt_pk_bf16_f32 v26, v30, v26
	v_cvt_pk_bf16_f32 v27, v32, v27
	v_cvt_pk_bf16_f32 v28, v50, v28
	v_cvt_pk_bf16_f32 v29, v52, v29
	s_and_b64 vcc, exec, s[10:11]
	global_store_dwordx4 v[42:43], v[26:29], off
	s_cbranch_vccnz .LBB0_639
	v_mov_b32_e32 v159, v143
	v_lshl_add_u64 v[26:27], v[46:47], 0, v[158:159]
	global_store_dwordx4 v[26:27], v[22:25], off offset:512 nt
	global_store_dwordx4 v[26:27], v[18:21], off offset:576 nt
.LBB0_639:
	s_nop 0
	v_pk_mul_f32 v[26:27], v[20:21], v[234:235]
	v_pk_mul_f32 v[28:29], v[18:19], v[232:233]
	v_pk_mul_f32 v[20:21], v[20:21], v[238:239]
	v_pk_mul_f32 v[18:19], v[18:19], v[236:237]
	v_pk_fma_f32 v[26:27], v[24:25], v[238:239], v[26:27] neg_lo:[0,0,1] neg_hi:[0,0,1]
	v_pk_fma_f32 v[28:29], v[22:23], v[236:237], v[28:29] neg_lo:[0,0,1] neg_hi:[0,0,1]
	v_pk_fma_f32 v[20:21], v[24:25], v[234:235], v[20:21]
	v_pk_fma_f32 v[18:19], v[22:23], v[232:233], v[18:19]
	v_pk_mul_f32 v[22:23], v[28:29], s[64:65] op_sel_hi:[1,0]
	v_pk_mul_f32 v[24:25], v[26:27], s[64:65] op_sel_hi:[1,0]
	v_pk_mul_f32 v[30:31], v[18:19], s[64:65] op_sel_hi:[1,0]
	v_pk_mul_f32 v[32:33], v[20:21], s[64:65] op_sel_hi:[1,0]
	v_cndmask_b32_e64 v30, v18, v30, s[6:7]
	v_cndmask_b32_e64 v21, v21, v33, s[6:7]
	v_cndmask_b32_e64 v32, v20, v32, s[6:7]
	v_cndmask_b32_e64 v20, v19, v31, s[6:7]
	v_cndmask_b32_e64 v19, v27, v25, s[6:7]
	v_cndmask_b32_e64 v24, v26, v24, s[6:7]
	v_cndmask_b32_e64 v18, v29, v23, s[6:7]
	v_cndmask_b32_e64 v22, v28, v22, s[6:7]
	v_cvt_pk_bf16_f32 v18, v22, v18
	v_cvt_pk_bf16_f32 v19, v24, v19
	v_cvt_pk_bf16_f32 v20, v30, v20
	v_cvt_pk_bf16_f32 v21, v32, v21
	s_and_b64 vcc, exec, s[8:9]
	v_add_u32_e32 v30, s67, v179
	global_store_dwordx4 v[42:43], v[18:21], off offset:256
	s_cbranch_vccnz .LBB0_643
	s_nop 0
	v_add_u32_e32 v26, s27, v179
	s_and_b64 vcc, exec, s[14:15]
	s_mov_b64 s[8:9], -1
	s_cbranch_vccz .LBB0_644

.LBB0_643:
	v_mov_b32_e32 v250, 1.0
	v_mov_b32_e32 v246, 0
	v_mov_b32_e32 v247, v246
	v_mov_b32_e32 v248, v246
	v_mov_b32_e32 v249, v246
	v_mov_b32_e32 v251, v250
	v_mov_b32_e32 v252, v250
	v_mov_b32_e32 v253, v250
	v_add_u32_e32 v26, s27, v179
	s_and_b64 vcc, exec, s[14:15]
	s_mov_b64 s[8:9], -1
	s_cbranch_vccnz .LBB0_641

.LBB0_651:
	v_lshl_add_u64 v[26:27], v[28:29], 0, s[24:25]
	s_nop 0
	v_pk_mul_f32 v[28:29], v[12:13], v[248:249]
	v_pk_mul_f32 v[32:33], v[10:11], v[246:247]
	v_pk_mul_f32 v[12:13], v[12:13], v[252:253]
	v_pk_mul_f32 v[10:11], v[10:11], v[250:251]
	v_pk_fma_f32 v[32:33], v[14:15], v[250:251], v[32:33] neg_lo:[0,0,1] neg_hi:[0,0,1]
	v_pk_fma_f32 v[28:29], v[16:17], v[252:253], v[28:29] neg_lo:[0,0,1] neg_hi:[0,0,1]
	v_pk_fma_f32 v[10:11], v[14:15], v[246:247], v[10:11]
	v_pk_fma_f32 v[12:13], v[16:17], v[248:249], v[12:13]
	s_mov_b32 s77, s25
	v_pk_mul_f32 v[14:15], v[32:33], s[64:65] op_sel_hi:[1,0]
	v_pk_mul_f32 v[16:17], v[28:29], s[64:65] op_sel_hi:[1,0]
	v_pk_mul_f32 v[34:35], v[10:11], s[64:65] op_sel_hi:[1,0]
	v_pk_mul_f32 v[36:37], v[12:13], s[64:65] op_sel_hi:[1,0]
	v_lshl_add_u64 v[26:27], v[26:27], 0, s[76:77]
	v_cndmask_b32_e64 v13, v13, v37, s[6:7]
	v_cndmask_b32_e64 v36, v12, v36, s[6:7]
	v_cndmask_b32_e64 v12, v11, v35, s[6:7]
	v_cndmask_b32_e64 v34, v10, v34, s[6:7]
	v_cndmask_b32_e64 v11, v29, v17, s[6:7]
	v_cndmask_b32_e64 v16, v28, v16, s[6:7]
	v_cndmask_b32_e64 v10, v33, v15, s[6:7]
	v_cndmask_b32_e64 v14, v32, v14, s[6:7]
	v_lshl_add_u64 v[26:27], v[26:27], 0, v[142:143]
	v_cvt_pk_bf16_f32 v10, v14, v10
	v_cvt_pk_bf16_f32 v11, v16, v11
	v_cvt_pk_bf16_f32 v12, v34, v12
	v_cvt_pk_bf16_f32 v13, v36, v13
	s_and_b64 vcc, exec, s[10:11]
	global_store_dwordx4 v[26:27], v[10:13], off
	s_cbranch_vccnz .LBB0_653
	v_mov_b32_e32 v159, v143
	v_lshl_add_u64 v[10:11], v[30:31], 0, v[158:159]
	global_store_dwordx4 v[10:11], v[6:9], off offset:512 nt
	global_store_dwordx4 v[10:11], v[2:5], off offset:576 nt
.LBB0_653:
	s_nop 0
	v_pk_mul_f32 v[10:11], v[4:5], v[248:249]
	v_pk_mul_f32 v[12:13], v[2:3], v[246:247]
	v_pk_mul_f32 v[4:5], v[4:5], v[252:253]
	v_pk_mul_f32 v[2:3], v[2:3], v[250:251]
	v_pk_fma_f32 v[10:11], v[8:9], v[252:253], v[10:11] neg_lo:[0,0,1] neg_hi:[0,0,1]
	v_pk_fma_f32 v[12:13], v[6:7], v[250:251], v[12:13] neg_lo:[0,0,1] neg_hi:[0,0,1]
	v_pk_fma_f32 v[4:5], v[8:9], v[248:249], v[4:5]
	v_pk_fma_f32 v[2:3], v[6:7], v[246:247], v[2:3]
	v_pk_mul_f32 v[6:7], v[12:13], s[64:65] op_sel_hi:[1,0]
	v_pk_mul_f32 v[8:9], v[10:11], s[64:65] op_sel_hi:[1,0]
	v_pk_mul_f32 v[14:15], v[2:3], s[64:65] op_sel_hi:[1,0]
	v_pk_mul_f32 v[16:17], v[4:5], s[64:65] op_sel_hi:[1,0]
	v_cndmask_b32_e64 v14, v2, v14, s[6:7]
	v_cndmask_b32_e64 v5, v5, v17, s[6:7]
	v_cndmask_b32_e64 v16, v4, v16, s[6:7]
	v_cndmask_b32_e64 v4, v3, v15, s[6:7]
	v_cndmask_b32_e64 v3, v11, v9, s[6:7]
	v_cndmask_b32_e64 v8, v10, v8, s[6:7]
	v_cndmask_b32_e64 v2, v13, v7, s[6:7]
	v_cndmask_b32_e64 v6, v12, v6, s[6:7]
	v_cvt_pk_bf16_f32 v2, v6, v2
	v_cvt_pk_bf16_f32 v3, v8, v3
	v_cvt_pk_bf16_f32 v4, v14, v4
	v_cvt_pk_bf16_f32 v5, v16, v5
	global_store_dwordx4 v[26:27], v[2:5], off offset:256
	s_andn2_b64 vcc, exec, s[4:5]
	s_mov_b64 s[4:5], -1
	s_cbranch_vccnz .LBB0_456

	.amdhsa_kernel _Z6fwd_mk4Args
		.amdhsa_group_segment_fixed_size 0
		.amdhsa_private_segment_fixed_size 0
		.amdhsa_kernarg_size 440
		.amdhsa_user_sgpr_count 2
		.amdhsa_user_sgpr_dispatch_ptr 0
		.amdhsa_user_sgpr_queue_ptr 0
		.amdhsa_user_sgpr_kernarg_segment_ptr 1
		.amdhsa_user_sgpr_dispatch_id 0
		.amdhsa_user_sgpr_kernarg_preload_length 0
		.amdhsa_user_sgpr_kernarg_preload_offset 0
		.amdhsa_user_sgpr_private_segment_size 0
		.amdhsa_uses_dynamic_stack 0
		.amdhsa_enable_private_segment 0
		.amdhsa_system_sgpr_workgroup_id_x 1
		.amdhsa_system_sgpr_workgroup_id_y 0
		.amdhsa_system_sgpr_workgroup_id_z 0
		.amdhsa_system_sgpr_workgroup_info 0
		.amdhsa_system_vgpr_workitem_id 0
		.amdhsa_next_free_vgpr 254
		.amdhsa_next_free_sgpr 102
		.amdhsa_accum_offset 256
		.amdhsa_reserve_vcc 1
		.amdhsa_float_round_mode_32 0
		.amdhsa_float_round_mode_16_64 0
		.amdhsa_float_denorm_mode_32 3
		.amdhsa_float_denorm_mode_16_64 3
		.amdhsa_dx10_clamp 1
		.amdhsa_ieee_mode 1
		.amdhsa_fp16_overflow 0
		.amdhsa_tg_split 0
		.amdhsa_exception_fp_ieee_invalid_op 0
		.amdhsa_exception_fp_denorm_src 0
		.amdhsa_exception_fp_ieee_div_zero 0
		.amdhsa_exception_fp_ieee_overflow 0
		.amdhsa_exception_fp_ieee_underflow 0
		.amdhsa_exception_fp_ieee_inexact 0
		.amdhsa_exception_int_div_zero 0
	.end_amdhsa_kernel

amdhsa.kernels:
  - .agpr_count:     0
    .args:
      - .offset:         0
        .size:           184
        .value_kind:     by_value
      - .offset:         184
        .size:           4
        .value_kind:     hidden_block_count_x
      - .offset:         188
        .size:           4
        .value_kind:     hidden_block_count_y
      - .offset:         192
        .size:           4
        .value_kind:     hidden_block_count_z
      - .offset:         196
        .size:           2
        .value_kind:     hidden_group_size_x
      - .offset:         198
        .size:           2
        .value_kind:     hidden_group_size_y
      - .offset:         200
        .size:           2
        .value_kind:     hidden_group_size_z
      - .offset:         202
        .size:           2
        .value_kind:     hidden_remainder_x
      - .offset:         204
        .size:           2
        .value_kind:     hidden_remainder_y
      - .offset:         206
        .size:           2
        .value_kind:     hidden_remainder_z
      - .offset:         224
        .size:           8
        .value_kind:     hidden_global_offset_x
      - .offset:         232
        .size:           8
        .value_kind:     hidden_global_offset_y
      - .offset:         240
        .size:           8
        .value_kind:     hidden_global_offset_z
      - .offset:         248
        .size:           2
        .value_kind:     hidden_grid_dims
      - .offset:         304
        .size:           4
        .value_kind:     hidden_dynamic_lds_size
    .group_segment_fixed_size: 0
    .kernarg_segment_align: 8
    .kernarg_segment_size: 440
    .language:       OpenCL C
    .language_version:
      - 2
      - 0
    .max_flat_workgroup_size: 512
    .name:           _Z6fwd_mk4Args
    .private_segment_fixed_size: 0
    .sgpr_count:     108
    .sgpr_spill_count: 10
    .symbol:         _Z6fwd_mk4Args.kd
    .uniform_work_group_size: 1
    .uses_dynamic_stack: false
    .vgpr_count:     254
    .vgpr_spill_count: 0
    .wavefront_size: 64
